# attention: next unit's K0/K1/K2 LDS-DMA and Q loads issued from the current unit's epilogue (and once before the unit loop); V0 stays in the prologue; on top of v55
# speedup vs baseline: 1.0015x; 1.0015x over previous
; template<int THRL,bool NOMAX> __device__ __forceinline__ void attn_unit(int b,int h,int qb,int t0,const bf16*Q,const bf16*__restrict__ KV,const bf16*__restrict__ GA,bf16*O,char*shm){
;     ...
;   const bf16*Qw=Q+(rowbase+q0+wid*QBLK)*QP+h*D;
;   const int kvh=h>>2; const bf16*Kh=KV+rowbase*KVP+kvh*D,*Vh=KV+rowbase*KVP+128+kvh*D;
;   const unsigned lds0=(unsigned)(uintptr_t)shm;
;   float*wsf=(float*)(shm+LDS_WS)+wid*64;
;   const bf16*ksrc=Kh+(long)lane*KVP+wid*8;
;   const bf16*vsrc=Vh+(long)(16*(wid&3)+(lane>>2))*KVP+(wid>>2)*32+(lane&3)*8;
;   const unsigned kdst=lds0+LDS_K+wid*1024, vdst=lds0+LDS_V+wid*1024;
;     ...
;   const int vb0=(int)(lds0+LDS_V)+((lane>>4)&1)*32+(lane&3)*8+(4*hi+((lane&15)>>2))*64;
;   const char*Kbase=shm+LDS_K; bf16x8 kf[8];
;   const lds_cptr shm3=(lds_cptr)shm; const lds_cptr kp0=shm3+LDS_K+hi*1024+r32*16; const lds_cptr vp0=shm3+LDS_V+((lane>>4)&1)*32+(lane&3)*8+(4*hi+((lane&15)>>2))*64;
;   const int NT=SEQ/KVBLK;
;   DMA_K(0,0);DMA_V(0,0);DMA_K(1,SLOTB);
;   bf16x8 qr[4];
;   #pragma unroll
;   for(int d0=0;d0<4;++d0)qr[d0]=*reinterpret_cast<const bf16x8*>(&Qw[(long)r32*QP+d0*16+hi*8]);
;   float mhat=0.f,l_reg=0.f;f32x16 o[2];o[0]=f32x16{};o[1]=f32x16{};f32x16 negm=f32x16{};asm volatile("":"+v"(negm));
;     ...
;   bool resc=false;
;     ...
;   f32x16 pA0,pA1,pB0,pB1;
;   int sl_prev=0,sl_cur=0,sl_next=SLOTB;
;     ...
;   DMA_K(2,2*SLOTB);
;     ...
;   {auto rr=__builtin_amdgcn_permlane32_swap(__float_as_uint(l_reg),__float_as_uint(l_reg),false,false);l_reg=__uint_as_float(rr[0])+__uint_as_float(rr[1]);}
;   if(hi==0)wsf[32+r32]=l_reg;asm volatile("s_waitcnt lgkmcnt(0)":::"memory");
;   float rli[16];
;   #pragma unroll
;   for(int r=0;r<16;++r)rli[r]=__builtin_amdgcn_rcpf(wsf[32+crow(r,hi)]);
;   bf16*Ow=O+(rowbase+q0+wid*QBLK)*QP+h*D; const bf16*Gw=GA+(rowbase+q0+wid*QBLK)*GP+h*D;
;   u32x4 gpre[4];
;   #pragma unroll
;   for(int i=0;i<4;++i)gpre[i]=*(const u32x4*)(Gw+(long)(i*8+(lane>>3))*GP+(lane&7)*8);
;   { float*stg=(float*)(shm+LDS_OST)+wid*2048;
;     #pragma unroll
;     for(int r=0;r<16;++r){const int orow=crow(r,hi);
;       #pragma unroll
;       for(int d0=0;d0<2;++d0)stg[orow*64+d0*32+r32]=o[d0][r]*rli[r];}
;     asm volatile("s_waitcnt lgkmcnt(0)":::"memory");
;     #pragma unroll
;     for(int i=0;i<4;++i){const int row=i*8+(lane>>3),ch=lane&7;
;       const f32x4_t a=*(const f32x4_t*)(stg+row*64+ch*8),c=*(const f32x4_t*)(stg+row*64+ch*8+4);
.LBB0_468:
	s_and_b64 vcc, exec, s[0:1]
	s_cbranch_vccz .LBB0_482
	s_mov_b32 s10, 0
	s_add_i32 s99, s10, 0
	s_cmp_lg_u64 s[18:19], 0
	s_cbranch_scc0 attn_pfa_modeb
	s_mul_i32 s0, s99, s3
	v_readlane_b32 s1, v254, 34
	s_nop 0
	s_add_i32 s6, s0, s1
	s_cmpk_lt_i32 s6, 0x400
	s_branch attn_pfa_have
attn_pfa_modeb:
	v_readlane_b32 s0, v254, 14
	s_nop 0
	s_or_b32 s6, s99, s0
	s_cmp_lt_u32 s99, 4
attn_pfa_have:
	s_cbranch_scc0 attn_pfa_end
	s_ashr_i32 s0, s6, 4
	s_and_b32 s1, s0, -8
	s_bfe_u32 s4, s6, 0x30004
	s_or_b32 s1, s1, s4
	s_lshr_b32 s0, s0, 29
	s_add_i32 s0, s1, s0
	s_ashr_i32 s8, s0, 3
	s_and_b32 s0, s0, -8
	s_ashr_i32 s9, s8, 31
	v_readfirstlane_b32 s12, v0
	s_lshl_b32 s4, s6, 8
	s_sub_i32 s13, s1, s0
	s_ashr_i32 s11, s12, 6
	s_lshl_b64 s[0:1], s[8:9], 12
	s_and_b32 s4, s4, 0xf00
	s_or_b32 s0, s0, s4
	s_lshl_b32 s4, s11, 5
	s_ashr_i32 s5, s4, 31
	s_add_u32 s0, s0, s4
	s_addc_u32 s1, s1, s5
	s_lshl_b64 s[0:1], s[0:1], 11
	s_add_u32 s14, s30, s0
	s_addc_u32 s15, s33, s1
	s_lshl_b32 s0, s13, 6
	s_ashr_i32 s1, s0, 31
	s_lshl_b64 s[6:7], s[0:1], 1
	s_add_u32 s0, s14, s6
	s_addc_u32 s1, s15, s7
	s_lshl_b64 s[8:9], s[8:9], 21
	s_add_u32 s14, s46, s8
	s_addc_u32 s15, s47, s9
	s_lshl_b32 s8, s13, 4
	s_andn2_b32 s8, s8, 63
	s_ashr_i32 s9, s8, 31
	s_lshl_b64 s[8:9], s[8:9], 1
	v_and_b32_e32 v184, 63, v0
	s_add_u32 s8, s14, s8
	s_addc_u32 s9, s15, s9
	v_mov_b32_e32 v207, 0
	v_lshlrev_b32_e32 v206, 9, v184
	v_lshl_add_u64 v[210:211], s[8:9], 0, v[206:207]
	s_lshl_b32 s14, s11, 3
	s_ashr_i32 s15, s14, 31
	v_readlane_b32 s20, v254, 52
	v_readlane_b32 s26, v254, 54
	v_lshl_add_u64 v[182:183], s[14:15], 1, v[210:211]
	s_lshl_b32 s13, s11, 10
	s_mov_b32 s21, s17
	s_mov_b32 s27, s17
	s_add_i32 s9, s13, 0
	v_lshl_add_u64 v[84:85], v[182:183], 0, s[20:21]
	s_mov_b32 m0, s9
	v_lshl_add_u64 v[210:211], v[182:183], 0, s[26:27]
	global_load_lds_dwordx4 v[84:85], off
	s_add_i32 m0, s9, 0x2000
	v_and_b32_e32 v185, 31, v0
	global_load_lds_dwordx4 v[210:211], off
	v_bfe_u32 v186, v0, 5, 1
	v_lshlrev_b32_e32 v206, 11, v185
	v_lshl_or_b32 v206, v186, 4, v206
	global_load_dwordx4 v[152:155], v206, s[0:1]
	global_load_dwordx4 v[144:147], v206, s[0:1] offset:32
	global_load_dwordx4 v[136:139], v206, s[0:1] offset:64
	global_load_dwordx4 v[132:135], v206, s[0:1] offset:96
	s_mov_b64 s[14:15], 0x10000
	s_add_i32 m0, s9, 0x4000
	v_lshl_add_u64 v[212:213], v[84:85], 0, s[14:15]
	global_load_lds_dwordx4 v[212:213], off
attn_pfa_end:
	s_branch .LBB0_472
.LBB0_470:
	s_or_b64 exec, exec, s[8:9]
	s_waitcnt lgkmcnt(0)
	v_lshl_add_u32 v2, v186, 4, s12
	ds_read_b128 v[36:39], v2 offset:49280
	ds_read_b128 v[40:43], v2 offset:49312
	s_lshl_b64 s[4:5], s[4:5], 1
	s_add_u32 s4, s84, s4
	s_addc_u32 s5, s85, s5
	s_waitcnt lgkmcnt(1)
	v_rcp_f32_e32 v52, v36
	v_rcp_f32_e32 v53, v37
	v_rcp_f32_e32 v54, v38
	v_rcp_f32_e32 v55, v39
	ds_read_b128 v[36:39], v2 offset:49344
	s_add_u32 s4, s4, s6
	v_and_b32_e32 v65, 56, v187
	s_waitcnt lgkmcnt(1)
	v_rcp_f32_e32 v56, v40
	v_rcp_f32_e32 v57, v41
	v_rcp_f32_e32 v58, v42
	v_rcp_f32_e32 v59, v43
	ds_read_b128 v[40:43], v2 offset:49376
	s_waitcnt lgkmcnt(1)
	v_rcp_f32_e32 v62, v38
	s_addc_u32 s5, s5, s7
	v_lshlrev_b32_e32 v2, 1, v65
	v_lshlrev_b32_e32 v38, 8, v184
	v_rcp_f32_e32 v60, v36
	v_rcp_f32_e32 v61, v37
	v_rcp_f32_e32 v63, v39
	v_lshl_add_u64 v[36:37], s[4:5], 0, v[2:3]
	v_and_b32_e32 v38, 0x3800, v38
	v_mov_b32_e32 v39, v3
	v_lshl_add_u64 v[36:37], v[36:37], 0, v[38:39]
	global_load_dwordx4 v[44:47], v[36:37], off
	s_movk_i32 s4, 0x4000
	v_add_co_u32_e32 v38, vcc, s4, v36
	s_mov_b32 s4, 0x8000
	s_nop 0
	v_addc_co_u32_e32 v39, vcc, 0, v37, vcc
	global_load_dwordx4 v[48:51], v[38:39], off
	v_add_co_u32_e32 v38, vcc, s4, v36
	s_mov_b32 s4, 0xc000
	s_nop 0
	v_addc_co_u32_e32 v39, vcc, 0, v37, vcc
	v_add_co_u32_e32 v36, vcc, s4, v36
	s_lshl_b32 s4, s11, 13
	s_add_i32 s4, s4, 0
	v_lshlrev_b32_e32 v69, 2, v185
	v_add3_u32 v69, s4, v188, v69
	v_addc_co_u32_e32 v37, vcc, 0, v37, vcc
	v_mul_f32_e32 v4, v4, v52
	v_mul_f32_e32 v20, v20, v52
	v_add_u32_e32 v52, 0xc800, v69
	s_waitcnt lgkmcnt(0)
	v_rcp_f32_e32 v64, v40
	v_rcp_f32_e32 v66, v41
	v_rcp_f32_e32 v67, v42
	v_rcp_f32_e32 v68, v43
	global_load_dwordx4 v[40:43], v[38:39], off
	s_nop 0
	global_load_dwordx4 v[36:39], v[36:37], off
	ds_write2_b32 v52, v4, v20 offset1:32
	v_mul_f32_e32 v4, v5, v53
	v_mul_f32_e32 v5, v21, v53
	ds_write2_b32 v52, v4, v5 offset0:64 offset1:96
	v_mul_f32_e32 v4, v6, v54
	v_mul_f32_e32 v5, v22, v54
	ds_write2_b32 v52, v4, v5 offset0:128 offset1:160
	v_mul_f32_e32 v4, v7, v55
	v_mul_f32_e32 v5, v23, v55
	ds_write2_b32 v52, v4, v5 offset0:192 offset1:224
	v_mul_f32_e32 v4, v8, v56
	v_mul_f32_e32 v5, v24, v56
	v_add_u32_e32 v6, 0xd000, v69
	ds_write2_b32 v6, v4, v5 offset1:32
	v_mul_f32_e32 v4, v9, v57
	v_mul_f32_e32 v5, v25, v57
	ds_write2_b32 v6, v4, v5 offset0:64 offset1:96
	v_mul_f32_e32 v4, v10, v58
	v_mul_f32_e32 v5, v26, v58
	ds_write2_b32 v6, v4, v5 offset0:128 offset1:160
	v_mul_f32_e32 v4, v11, v59
	v_mul_f32_e32 v5, v27, v59
	ds_write2_b32 v6, v4, v5 offset0:192 offset1:224
	v_mul_f32_e32 v4, v12, v60
	v_mul_f32_e32 v5, v28, v60
	v_add_u32_e32 v6, 0xd800, v69
	ds_write2_b32 v6, v4, v5 offset1:32
	v_mul_f32_e32 v4, v13, v61
	v_mul_f32_e32 v5, v29, v61
	ds_write2_b32 v6, v4, v5 offset0:64 offset1:96
	v_mul_f32_e32 v4, v14, v62
	v_mul_f32_e32 v5, v30, v62
	ds_write2_b32 v6, v4, v5 offset0:128 offset1:160
	v_mul_f32_e32 v4, v15, v63
	v_mul_f32_e32 v5, v31, v63
	ds_write2_b32 v6, v4, v5 offset0:192 offset1:224
	v_mul_f32_e32 v4, v16, v64
	v_mul_f32_e32 v5, v32, v64
	v_add_u32_e32 v6, 0xe000, v69
	ds_write2_b32 v6, v4, v5 offset1:32
	v_mul_f32_e32 v4, v17, v66
	v_mul_f32_e32 v5, v33, v66
	ds_write2_b32 v6, v4, v5 offset0:64 offset1:96
	v_mul_f32_e32 v4, v18, v67
	v_mul_f32_e32 v5, v34, v67
	ds_write2_b32 v6, v4, v5 offset0:128 offset1:160
	v_mul_f32_e32 v4, v19, v68
	v_mul_f32_e32 v5, v35, v68
	ds_write2_b32 v6, v4, v5 offset0:192 offset1:224
	v_lshrrev_b32_e32 v22, 3, v184
	v_lshl_add_u32 v23, v65, 2, s4
	s_waitcnt vmcnt(3)
	v_lshlrev_b32_e32 v14, 16, v44
	v_and_b32_e32 v15, 0xffff0000, v44
	v_mul_f32_e32 v6, 0xbfb8aa3b, v14
	v_exp_f32_e32 v16, v6
	v_mul_f32_e32 v6, 0xbfb8aa3b, v15
	v_exp_f32_e32 v17, v6
	s_waitcnt lgkmcnt(0)
	v_lshl_add_u64 v[4:5], s[0:1], 0, v[2:3]
	s_add_i32 s99, s10, 1
	s_cmp_lg_u64 s[18:19], 0
	s_cbranch_scc0 attn_pfb_modeb
	s_mul_i32 s0, s99, s3
	v_readlane_b32 s1, v254, 34
	s_nop 0
	s_add_i32 s6, s0, s1
	s_cmpk_lt_i32 s6, 0x400
	s_branch attn_pfb_have
; __device__ __forceinline__ unsigned cvtpk_s(float lo,float hi){f32x2_t v={lo,hi};bf16x2_t b=__builtin_convertvector(v,bf16x2_t);return __builtin_bit_cast(unsigned,b);}
;   #define DMA_K(t,slot) glds16(ksrc+(long)(((t)+t0)&(NT-1))*KVBLK*KVP,(unsigned)__builtin_amdgcn_readfirstlane(kdst+(slot)))
; template<int THRL,bool NOMAX> __device__ __forceinline__ void attn_unit(int b,int h,int qb,int t0,const bf16*Q,const bf16*__restrict__ KV,const bf16*__restrict__ GA,bf16*O,char*shm){
;     ...
;   const bf16*Qw=Q+(rowbase+q0+wid*QBLK)*QP+h*D;
;   const int kvh=h>>2; const bf16*Kh=KV+rowbase*KVP+kvh*D,*Vh=KV+rowbase*KVP+128+kvh*D;
;   const unsigned lds0=(unsigned)(uintptr_t)shm;
;   float*wsf=(float*)(shm+LDS_WS)+wid*64;
;   const bf16*ksrc=Kh+(long)lane*KVP+wid*8;
;   const bf16*vsrc=Vh+(long)(16*(wid&3)+(lane>>2))*KVP+(wid>>2)*32+(lane&3)*8;
;   const unsigned kdst=lds0+LDS_K+wid*1024, vdst=lds0+LDS_V+wid*1024;
;     ...
;   const int vb0=(int)(lds0+LDS_V)+((lane>>4)&1)*32+(lane&3)*8+(4*hi+((lane&15)>>2))*64;
;   const char*Kbase=shm+LDS_K; bf16x8 kf[8];
;   const lds_cptr shm3=(lds_cptr)shm; const lds_cptr kp0=shm3+LDS_K+hi*1024+r32*16; const lds_cptr vp0=shm3+LDS_V+((lane>>4)&1)*32+(lane&3)*8+(4*hi+((lane&15)>>2))*64;
;   const int NT=SEQ/KVBLK;
;   DMA_K(0,0);DMA_V(0,0);DMA_K(1,SLOTB);
;   bf16x8 qr[4];
;   #pragma unroll
;   for(int d0=0;d0<4;++d0)qr[d0]=*reinterpret_cast<const bf16x8*>(&Qw[(long)r32*QP+d0*16+hi*8]);
;   float mhat=0.f,l_reg=0.f;f32x16 o[2];o[0]=f32x16{};o[1]=f32x16{};f32x16 negm=f32x16{};asm volatile("":"+v"(negm));
;     ...
;   bool resc=false;
;     ...
;   f32x16 pA0,pA1,pB0,pB1;
;   int sl_prev=0,sl_cur=0,sl_next=SLOTB;
;     ...
;   DMA_K(2,2*SLOTB);
;     ...
;     for(int i=0;i<4;++i){const int row=i*8+(lane>>3),ch=lane&7;
;       const f32x4_t a=*(const f32x4_t*)(stg+row*64+ch*8),c=*(const f32x4_t*)(stg+row*64+ch*8+4);
;       const u32x4 g=gpre[i]; u32x4 v;
;     ...
;       const float g0=__uint_as_float(g.x<<16),g1=__uint_as_float(g.x&0xffff0000u),g2=__uint_as_float(g.y<<16),g3=__uint_as_float(g.y&0xffff0000u),g4=__uint_as_float(g.z<<16),g5=__uint_as_float(g.z&0xffff0000u),g6=__uint_as_float(g.w<<16),g7=__uint_as_float(g.w&0xffff0000u);
;       v.x=cvtpk_s(a[0]*SILU_(g0),a[1]*SILU_(g1)); v.y=cvtpk_s(a[2]*SILU_(g2),a[3]*SILU_(g3));
;       v.z=cvtpk_s(c[0]*SILU_(g4),c[1]*SILU_(g5)); v.w=cvtpk_s(c[2]*SILU_(g6),c[3]*SILU_(g7));
;     ...
;       ATTN_STORE16(Ow+(long)row*QP+ch*8,v);} }
attn_pfb_modeb:
	v_readlane_b32 s0, v254, 14
	s_nop 0
	s_or_b32 s6, s99, s0
	s_cmp_lt_u32 s99, 4
attn_pfb_have:
	s_cbranch_scc0 attn_pfb_dummy
	s_ashr_i32 s0, s6, 4
	s_and_b32 s1, s0, -8
	s_bfe_u32 s4, s6, 0x30004
	s_or_b32 s1, s1, s4
	s_lshr_b32 s0, s0, 29
	s_add_i32 s0, s1, s0
	s_ashr_i32 s8, s0, 3
	s_and_b32 s0, s0, -8
	s_ashr_i32 s9, s8, 31
	v_readfirstlane_b32 s12, v0
	s_lshl_b32 s4, s6, 8
	s_sub_i32 s13, s1, s0
	s_ashr_i32 s11, s12, 6
	s_lshl_b64 s[0:1], s[8:9], 12
	s_and_b32 s4, s4, 0xf00
	s_or_b32 s0, s0, s4
	s_lshl_b32 s4, s11, 5
	s_ashr_i32 s5, s4, 31
	s_add_u32 s0, s0, s4
	s_addc_u32 s1, s1, s5
	s_lshl_b64 s[0:1], s[0:1], 11
	s_add_u32 s14, s30, s0
	s_addc_u32 s15, s33, s1
	s_lshl_b32 s0, s13, 6
	s_ashr_i32 s1, s0, 31
	s_lshl_b64 s[6:7], s[0:1], 1
	s_add_u32 s0, s14, s6
	s_addc_u32 s1, s15, s7
	s_lshl_b64 s[8:9], s[8:9], 21
	s_add_u32 s14, s46, s8
	s_addc_u32 s15, s47, s9
	s_lshl_b32 s8, s13, 4
	s_andn2_b32 s8, s8, 63
	s_ashr_i32 s9, s8, 31
	s_lshl_b64 s[8:9], s[8:9], 1
	v_and_b32_e32 v184, 63, v0
	s_add_u32 s8, s14, s8
	s_addc_u32 s9, s15, s9
	v_mov_b32_e32 v207, 0
	v_lshlrev_b32_e32 v206, 9, v184
	v_lshl_add_u64 v[210:211], s[8:9], 0, v[206:207]
	s_lshl_b32 s14, s11, 3
	s_ashr_i32 s15, s14, 31
	v_readlane_b32 s20, v254, 52
	v_readlane_b32 s26, v254, 54
	v_lshl_add_u64 v[182:183], s[14:15], 1, v[210:211]
	s_lshl_b32 s13, s11, 10
	s_mov_b32 s21, s17
	s_mov_b32 s27, s17
	s_add_i32 s9, s13, 0
	v_lshl_add_u64 v[84:85], v[182:183], 0, s[20:21]
	s_mov_b32 m0, s9
	v_lshl_add_u64 v[210:211], v[182:183], 0, s[26:27]
	global_load_lds_dwordx4 v[84:85], off
	s_add_i32 m0, s9, 0x2000
	v_and_b32_e32 v185, 31, v0
	global_load_lds_dwordx4 v[210:211], off
	v_bfe_u32 v186, v0, 5, 1
	v_lshlrev_b32_e32 v206, 11, v185
	v_lshl_or_b32 v206, v186, 4, v206
	global_load_dwordx4 v[152:155], v206, s[0:1]
	global_load_dwordx4 v[144:147], v206, s[0:1] offset:32
	global_load_dwordx4 v[136:139], v206, s[0:1] offset:64
	global_load_dwordx4 v[132:135], v206, s[0:1] offset:96
	s_mov_b64 s[14:15], 0x10000
	s_add_i32 m0, s9, 0x4000
	v_lshl_add_u64 v[212:213], v[84:85], 0, s[14:15]
	global_load_lds_dwordx4 v[212:213], off
	s_branch attn_pfb_end
attn_pfb_dummy:
	global_load_dword v214, v3, s[84:85]
	global_load_dword v214, v3, s[84:85]
	global_load_dword v214, v3, s[84:85]
	global_load_dword v214, v3, s[84:85]
	global_load_dword v214, v3, s[84:85]
	global_load_dword v214, v3, s[84:85]
	global_load_dword v214, v3, s[84:85]
attn_pfb_end:
	v_lshl_add_u32 v2, v22, 8, v23
	ds_read_b128 v[6:9], v2 offset:51200
	ds_read_b128 v[10:13], v2 offset:51216
	v_add_f32_e32 v2, 1.0, v16
	v_lshlrev_b32_e32 v18, 16, v45
	v_rcp_f32_e32 v16, v2
	v_add_f32_e32 v2, 1.0, v17
	v_and_b32_e32 v19, 0xffff0000, v45
	v_mul_f32_e32 v17, 0xbfb8aa3b, v18
	v_exp_f32_e32 v20, v17
	v_mul_f32_e32 v17, 0xbfb8aa3b, v19
	v_exp_f32_e32 v21, v17
	v_rcp_f32_e32 v17, v2
	v_add_f32_e32 v2, 1.0, v20
	v_rcp_f32_e32 v20, v2
	v_add_f32_e32 v2, 1.0, v21
	v_rcp_f32_e32 v21, v2
	v_pk_mul_f32 v[14:15], v[16:17], v[14:15]
	v_and_b32_e32 v17, 0xffff0000, v47
	s_waitcnt lgkmcnt(1)
	v_pk_mul_f32 v[6:7], v[14:15], v[6:7]
	v_pk_mul_f32 v[14:15], v[20:21], v[18:19]
	v_cvt_pk_bf16_f32 v6, v6, v7
	v_pk_mul_f32 v[8:9], v[14:15], v[8:9]
	v_lshlrev_b32_e32 v14, 16, v46
	v_and_b32_e32 v15, 0xffff0000, v46
	v_mul_f32_e32 v2, 0xbfb8aa3b, v14
	v_exp_f32_e32 v2, v2
	v_mul_f32_e32 v7, 0xbfb8aa3b, v15
	v_exp_f32_e32 v16, v7
	v_cvt_pk_bf16_f32 v7, v8, v9
	v_add_f32_e32 v2, 1.0, v2
	v_rcp_f32_e32 v8, v2
	v_add_f32_e32 v2, 1.0, v16
	v_lshlrev_b32_e32 v16, 16, v47
	v_mul_f32_e32 v9, 0xbfb8aa3b, v16
	v_exp_f32_e32 v18, v9
	v_mul_f32_e32 v9, 0xbfb8aa3b, v17
	v_exp_f32_e32 v19, v9
	v_rcp_f32_e32 v9, v2
	v_add_f32_e32 v2, 1.0, v18
	v_rcp_f32_e32 v18, v2
	v_add_f32_e32 v2, 1.0, v19
	v_rcp_f32_e32 v19, v2
	v_pk_mul_f32 v[8:9], v[8:9], v[14:15]
	v_lshlrev_b32_e32 v2, 11, v22
	s_waitcnt lgkmcnt(0)
	v_pk_mul_f32 v[8:9], v[8:9], v[10:11]
	v_pk_mul_f32 v[10:11], v[18:19], v[16:17]
	v_cvt_pk_bf16_f32 v8, v8, v9
	v_pk_mul_f32 v[10:11], v[10:11], v[12:13]
	s_waitcnt vmcnt(9)
	v_lshlrev_b32_e32 v14, 16, v48
	v_cvt_pk_bf16_f32 v9, v10, v11
	v_lshl_add_u64 v[10:11], v[4:5], 0, v[2:3]
	global_store_dwordx4 v[10:11], v[6:9], off
	v_and_b32_e32 v15, 0xffff0000, v48
	v_lshlrev_b32_e32 v18, 16, v49
	v_mul_f32_e32 v6, 0xbfb8aa3b, v14
	v_exp_f32_e32 v16, v6
	v_mul_f32_e32 v6, 0xbfb8aa3b, v15
	v_and_b32_e32 v19, 0xffff0000, v49
	v_exp_f32_e32 v17, v6
	v_mul_f32_e32 v20, 0xbfb8aa3b, v18
	v_mul_f32_e32 v21, 0xbfb8aa3b, v19
	v_exp_f32_e32 v20, v20
	v_exp_f32_e32 v21, v21
	v_or_b32_e32 v2, 8, v22
	v_add_f32_e32 v16, 1.0, v16
	v_add_f32_e32 v17, 1.0, v17
	v_lshl_add_u32 v10, v2, 8, v23
	v_rcp_f32_e32 v16, v16
	v_rcp_f32_e32 v17, v17
	v_add_f32_e32 v20, 1.0, v20
	v_add_f32_e32 v21, 1.0, v21
	ds_read_b128 v[6:9], v10 offset:51200
	ds_read_b128 v[10:13], v10 offset:51216
	v_rcp_f32_e32 v20, v20
	v_rcp_f32_e32 v21, v21
	v_pk_mul_f32 v[14:15], v[16:17], v[14:15]
	v_lshlrev_b32_e32 v2, 11, v2
	s_waitcnt lgkmcnt(1)
; __device__ __forceinline__ unsigned cvtpk_s(float lo,float hi){f32x2_t v={lo,hi};bf16x2_t b=__builtin_convertvector(v,bf16x2_t);return __builtin_bit_cast(unsigned,b);}
;       #define SILU_(x) ((x)*__builtin_amdgcn_rcpf(1.f+__builtin_amdgcn_exp2f(-1.4426950408889634f*(x))))
; #define SILU_(x) ((x) * __builtin_amdgcn_rcpf(1.f + __builtin_amdgcn_exp2f(-1.4426950408889634f * (x))))
; template<int THRL,bool NOMAX> __device__ __forceinline__ void attn_unit(int b,int h,int qb,int t0,const bf16*Q,const bf16*__restrict__ KV,const bf16*__restrict__ GA,bf16*O,char*shm){
;     ...
;     for(int i=0;i<4;++i){const int row=i*8+(lane>>3),ch=lane&7;
;       const f32x4_t a=*(const f32x4_t*)(stg+row*64+ch*8),c=*(const f32x4_t*)(stg+row*64+ch*8+4);
;       const u32x4 g=gpre[i]; u32x4 v;
;     ...
;       const float g0=__uint_as_float(g.x<<16),g1=__uint_as_float(g.x&0xffff0000u),g2=__uint_as_float(g.y<<16),g3=__uint_as_float(g.y&0xffff0000u),g4=__uint_as_float(g.z<<16),g5=__uint_as_float(g.z&0xffff0000u),g6=__uint_as_float(g.w<<16),g7=__uint_as_float(g.w&0xffff0000u);
;       v.x=cvtpk_s(a[0]*SILU_(g0),a[1]*SILU_(g1)); v.y=cvtpk_s(a[2]*SILU_(g2),a[3]*SILU_(g3));
;       v.z=cvtpk_s(c[0]*SILU_(g4),c[1]*SILU_(g5)); v.w=cvtpk_s(c[2]*SILU_(g6),c[3]*SILU_(g7));
;     ...
;       ATTN_STORE16(Ow+(long)row*QP+ch*8,v);} }
;   asm volatile("s_waitcnt lgkmcnt(0)\n\ts_barrier":::"memory");
;     ...
;   for(int i=0;S.next(i,u);++i){ S.a_ready(u); attn_unit<THRL,NOMAX>(u.bh/NHEAD,u.bh%NHEAD,u.qb,u.t0,T.Q,T.KV,T.GA,T.O,lds); S.done(u); }
	v_pk_mul_f32 v[6:7], v[14:15], v[6:7]
	v_pk_mul_f32 v[14:15], v[20:21], v[18:19]
	v_cvt_pk_bf16_f32 v6, v6, v7
	v_pk_mul_f32 v[8:9], v[14:15], v[8:9]
	v_lshlrev_b32_e32 v14, 16, v50
	v_and_b32_e32 v15, 0xffff0000, v50
	v_mul_f32_e32 v7, 0xbfb8aa3b, v14
	v_exp_f32_e32 v16, v7
	v_mul_f32_e32 v7, 0xbfb8aa3b, v15
	v_exp_f32_e32 v17, v7
	v_cvt_pk_bf16_f32 v7, v8, v9
	v_add_f32_e32 v8, 1.0, v16
	v_lshlrev_b32_e32 v16, 16, v51
	v_add_f32_e32 v9, 1.0, v17
	v_and_b32_e32 v17, 0xffff0000, v51
	v_mul_f32_e32 v18, 0xbfb8aa3b, v16
	v_mul_f32_e32 v19, 0xbfb8aa3b, v17
	v_exp_f32_e32 v18, v18
	v_exp_f32_e32 v19, v19
	v_rcp_f32_e32 v8, v8
	v_rcp_f32_e32 v9, v9
	v_add_f32_e32 v18, 1.0, v18
	v_add_f32_e32 v19, 1.0, v19
	v_rcp_f32_e32 v18, v18
	v_rcp_f32_e32 v19, v19
	v_pk_mul_f32 v[8:9], v[8:9], v[14:15]
	s_waitcnt vmcnt(9)
	v_lshlrev_b32_e32 v14, 16, v40
	s_waitcnt lgkmcnt(0)
	v_pk_mul_f32 v[8:9], v[8:9], v[10:11]
	v_pk_mul_f32 v[10:11], v[18:19], v[16:17]
	v_cvt_pk_bf16_f32 v8, v8, v9
	v_pk_mul_f32 v[10:11], v[10:11], v[12:13]
	v_and_b32_e32 v15, 0xffff0000, v40
	v_cvt_pk_bf16_f32 v9, v10, v11
	v_lshl_add_u64 v[10:11], v[4:5], 0, v[2:3]
	global_store_dwordx4 v[10:11], v[6:9], off
	v_lshlrev_b32_e32 v18, 16, v41
	v_and_b32_e32 v19, 0xffff0000, v41
	v_mul_f32_e32 v6, 0xbfb8aa3b, v14
	v_exp_f32_e32 v16, v6
	v_mul_f32_e32 v6, 0xbfb8aa3b, v15
	v_exp_f32_e32 v17, v6
	v_mul_f32_e32 v20, 0xbfb8aa3b, v18
	v_mul_f32_e32 v21, 0xbfb8aa3b, v19
	v_exp_f32_e32 v20, v20
	v_exp_f32_e32 v21, v21
	v_or_b32_e32 v2, 16, v22
	v_add_f32_e32 v16, 1.0, v16
	v_add_f32_e32 v17, 1.0, v17
	v_lshl_add_u32 v10, v2, 8, v23
	v_rcp_f32_e32 v16, v16
	v_rcp_f32_e32 v17, v17
	v_add_f32_e32 v20, 1.0, v20
	v_add_f32_e32 v21, 1.0, v21
	ds_read_b128 v[6:9], v10 offset:51200
	ds_read_b128 v[10:13], v10 offset:51216
	v_rcp_f32_e32 v20, v20
	v_rcp_f32_e32 v21, v21
	v_pk_mul_f32 v[14:15], v[16:17], v[14:15]
	v_lshlrev_b32_e32 v2, 11, v2
	s_waitcnt lgkmcnt(1)
	v_pk_mul_f32 v[6:7], v[14:15], v[6:7]
	v_pk_mul_f32 v[14:15], v[20:21], v[18:19]
	v_cvt_pk_bf16_f32 v6, v6, v7
	v_pk_mul_f32 v[8:9], v[14:15], v[8:9]
	v_lshlrev_b32_e32 v14, 16, v42
	v_and_b32_e32 v15, 0xffff0000, v42
	v_mul_f32_e32 v7, 0xbfb8aa3b, v14
	v_exp_f32_e32 v16, v7
	v_mul_f32_e32 v7, 0xbfb8aa3b, v15
	v_exp_f32_e32 v17, v7
	v_cvt_pk_bf16_f32 v7, v8, v9
	v_add_f32_e32 v8, 1.0, v16
	v_lshlrev_b32_e32 v16, 16, v43
	v_add_f32_e32 v9, 1.0, v17
	v_and_b32_e32 v17, 0xffff0000, v43
	v_mul_f32_e32 v18, 0xbfb8aa3b, v16
	v_mul_f32_e32 v19, 0xbfb8aa3b, v17
	v_exp_f32_e32 v18, v18
	v_exp_f32_e32 v19, v19
	v_rcp_f32_e32 v8, v8
	v_rcp_f32_e32 v9, v9
	v_add_f32_e32 v18, 1.0, v18
	v_add_f32_e32 v19, 1.0, v19
	v_rcp_f32_e32 v18, v18
	v_rcp_f32_e32 v19, v19
	v_pk_mul_f32 v[8:9], v[8:9], v[14:15]
	s_waitcnt vmcnt(9)
	v_lshlrev_b32_e32 v14, 16, v36
	s_waitcnt lgkmcnt(0)
	v_pk_mul_f32 v[8:9], v[8:9], v[10:11]
	v_pk_mul_f32 v[10:11], v[18:19], v[16:17]
	v_cvt_pk_bf16_f32 v8, v8, v9
	v_pk_mul_f32 v[10:11], v[10:11], v[12:13]
	v_and_b32_e32 v15, 0xffff0000, v36
	v_cvt_pk_bf16_f32 v9, v10, v11
	v_lshl_add_u64 v[10:11], v[4:5], 0, v[2:3]
	global_store_dwordx4 v[10:11], v[6:9], off
	v_lshlrev_b32_e32 v18, 16, v37
	v_and_b32_e32 v19, 0xffff0000, v37
	v_mul_f32_e32 v6, 0xbfb8aa3b, v14
	v_exp_f32_e32 v16, v6
	v_mul_f32_e32 v6, 0xbfb8aa3b, v15
	v_exp_f32_e32 v17, v6
	v_mul_f32_e32 v20, 0xbfb8aa3b, v18
	v_mul_f32_e32 v21, 0xbfb8aa3b, v19
	v_exp_f32_e32 v20, v20
	v_exp_f32_e32 v21, v21
	v_or_b32_e32 v2, 24, v22
	v_add_f32_e32 v16, 1.0, v16
	v_add_f32_e32 v17, 1.0, v17
	v_lshl_add_u32 v10, v2, 8, v23
	v_rcp_f32_e32 v16, v16
	v_rcp_f32_e32 v17, v17
	v_add_f32_e32 v20, 1.0, v20
	v_add_f32_e32 v21, 1.0, v21
	ds_read_b128 v[6:9], v10 offset:51200
	ds_read_b128 v[10:13], v10 offset:51216
	v_rcp_f32_e32 v20, v20
	v_rcp_f32_e32 v21, v21
	v_pk_mul_f32 v[14:15], v[16:17], v[14:15]
	v_lshlrev_b32_e32 v2, 11, v2
	s_waitcnt lgkmcnt(1)
	v_pk_mul_f32 v[6:7], v[14:15], v[6:7]
	v_pk_mul_f32 v[14:15], v[20:21], v[18:19]
	v_cvt_pk_bf16_f32 v6, v6, v7
	v_pk_mul_f32 v[8:9], v[14:15], v[8:9]
	v_lshlrev_b32_e32 v14, 16, v38
	v_and_b32_e32 v15, 0xffff0000, v38
	v_mul_f32_e32 v7, 0xbfb8aa3b, v14
	v_exp_f32_e32 v16, v7
	v_mul_f32_e32 v7, 0xbfb8aa3b, v15
	v_exp_f32_e32 v17, v7
	v_cvt_pk_bf16_f32 v7, v8, v9
	v_add_f32_e32 v8, 1.0, v16
	v_lshlrev_b32_e32 v16, 16, v39
	v_add_f32_e32 v9, 1.0, v17
	v_and_b32_e32 v17, 0xffff0000, v39
	v_mul_f32_e32 v18, 0xbfb8aa3b, v16
	v_mul_f32_e32 v19, 0xbfb8aa3b, v17
	v_exp_f32_e32 v18, v18
	v_exp_f32_e32 v19, v19
	v_rcp_f32_e32 v8, v8
	v_rcp_f32_e32 v9, v9
	v_add_f32_e32 v18, 1.0, v18
	v_add_f32_e32 v19, 1.0, v19
	v_rcp_f32_e32 v18, v18
	v_rcp_f32_e32 v19, v19
	v_pk_mul_f32 v[8:9], v[8:9], v[14:15]
	v_lshl_add_u64 v[4:5], v[4:5], 0, v[2:3]
	s_waitcnt lgkmcnt(0)
	v_pk_mul_f32 v[8:9], v[8:9], v[10:11]
	v_pk_mul_f32 v[10:11], v[18:19], v[16:17]
	v_cvt_pk_bf16_f32 v8, v8, v9
	v_pk_mul_f32 v[10:11], v[10:11], v[12:13]
	s_add_i32 s10, s10, 1
	v_cvt_pk_bf16_f32 v9, v10, v11
	global_store_dwordx4 v[4:5], v[6:9], off
	s_waitcnt lgkmcnt(0)
	s_barrier
	s_mov_b64 s[4:5], 0

;   #define DMA_K(t,slot) glds16(ksrc+(long)(((t)+t0)&(NT-1))*KVBLK*KVP,(unsigned)__builtin_amdgcn_readfirstlane(kdst+(slot)))
;   #define DMA_V(t,slot) glds16(vsrc+(long)(((t)+t0)&(NT-1))*KVBLK*KVP,(unsigned)__builtin_amdgcn_readfirstlane(vdst+(slot)))
; template<int THRL,bool NOMAX> __device__ __forceinline__ void attn_unit(int b,int h,int qb,int t0,const bf16*Q,const bf16*__restrict__ KV,const bf16*__restrict__ GA,bf16*O,char*shm){
;   int tid_=threadIdx.x; asm volatile("":"+v"(tid_)); const int tid=tid_,lane=tid&63,r32=lane&31,hi=lane>>5; const int wid=__builtin_amdgcn_readfirstlane(tid>>6);
;   const long rowbase=(long)b*SEQ; const int q0=qb*QB;
;   const bf16*Qw=Q+(rowbase+q0+wid*QBLK)*QP+h*D;
;   const int kvh=h>>2; const bf16*Kh=KV+rowbase*KVP+kvh*D,*Vh=KV+rowbase*KVP+128+kvh*D;
;   const unsigned lds0=(unsigned)(uintptr_t)shm;
;   float*wsf=(float*)(shm+LDS_WS)+wid*64;
;   const bf16*ksrc=Kh+(long)lane*KVP+wid*8;
;   const bf16*vsrc=Vh+(long)(16*(wid&3)+(lane>>2))*KVP+(wid>>2)*32+(lane&3)*8;
;   const unsigned kdst=lds0+LDS_K+wid*1024, vdst=lds0+LDS_V+wid*1024;
;     ...
;   const int vb0=(int)(lds0+LDS_V)+((lane>>4)&1)*32+(lane&3)*8+(4*hi+((lane&15)>>2))*64;
;   const char*Kbase=shm+LDS_K; bf16x8 kf[8];
;   const lds_cptr shm3=(lds_cptr)shm; const lds_cptr kp0=shm3+LDS_K+hi*1024+r32*16; const lds_cptr vp0=shm3+LDS_V+((lane>>4)&1)*32+(lane&3)*8+(4*hi+((lane&15)>>2))*64;
;   const int NT=SEQ/KVBLK;
;   DMA_K(0,0);DMA_V(0,0);DMA_K(1,SLOTB);
;   bf16x8 qr[4];
;   #pragma unroll
;   for(int d0=0;d0<4;++d0)qr[d0]=*reinterpret_cast<const bf16x8*>(&Qw[(long)r32*QP+d0*16+hi*8]);
;   float mhat=0.f,l_reg=0.f;f32x16 o[2];o[0]=f32x16{};o[1]=f32x16{};f32x16 negm=f32x16{};asm volatile("":"+v"(negm));
.LBB0_477:
	s_mov_b64 s[4:5], -1
	s_and_b64 vcc, exec, s[0:1]
	s_cbranch_vccz .LBB0_471
	s_ashr_i32 s0, s6, 4
	s_and_b32 s1, s0, -8
	s_bfe_u32 s4, s6, 0x30004
	s_or_b32 s1, s1, s4
	s_lshr_b32 s0, s0, 29
	s_add_i32 s0, s1, s0
	s_ashr_i32 s8, s0, 3
	v_mov_b32_e32 v44, v0
	s_and_b32 s0, s0, -8
	s_ashr_i32 s9, s8, 31
	v_readfirstlane_b32 s12, v44
	s_lshl_b32 s4, s6, 8
	s_sub_i32 s13, s1, s0
	s_ashr_i32 s11, s12, 6
	s_lshl_b64 s[0:1], s[8:9], 12
	s_and_b32 s4, s4, 0xf00
	s_or_b32 s0, s0, s4
	s_lshl_b32 s4, s11, 5
	s_ashr_i32 s5, s4, 31
	s_add_u32 s0, s0, s4
	s_addc_u32 s1, s1, s5
	s_lshl_b64 s[4:5], s[0:1], 10
	s_lshl_b64 s[0:1], s[0:1], 11
	s_add_u32 s14, s30, s0
	s_addc_u32 s15, s33, s1
	s_lshl_b32 s0, s13, 6
	s_ashr_i32 s1, s0, 31
	s_lshl_b64 s[6:7], s[0:1], 1
	s_add_u32 s0, s14, s6
	s_addc_u32 s1, s15, s7
	s_lshl_b64 s[8:9], s[8:9], 21
	s_add_u32 s14, s46, s8
	s_addc_u32 s15, s47, s9
	s_lshl_b32 s8, s13, 4
	s_andn2_b32 s8, s8, 63
	s_ashr_i32 s9, s8, 31
	s_lshl_b64 s[8:9], s[8:9], 1
	v_and_b32_e32 v184, 63, v44
	s_add_u32 s8, s14, s8
	s_addc_u32 s9, s15, s9
	v_lshlrev_b32_e32 v2, 9, v184
	v_lshl_add_u64 v[4:5], s[8:9], 0, v[2:3]
	s_lshl_b32 s13, s11, 4
	v_bfe_u32 v2, v44, 2, 4
	s_lshl_b32 s14, s11, 3
	v_and_or_b32 v2, s13, 48, v2
	s_ashr_i32 s15, s14, 31
	v_lshlrev_b32_e32 v2, 9, v2
	v_lshl_add_u64 v[182:183], s[14:15], 1, v[4:5]
	v_lshl_add_u64 v[4:5], s[8:9], 0, v[2:3]
	s_ashr_i32 s8, s12, 3
	s_andn2_b32 s8, s8, 31
	s_ashr_i32 s9, s8, 31
	s_lshl_b32 s13, s11, 10
	v_readlane_b32 s20, v254, 52
	s_cmp_lg_u32 0, -1
	v_readlane_b32 s21, v254, 53
	v_lshl_add_u64 v[4:5], s[8:9], 1, v[4:5]
	s_cselect_b32 s8, 0, 0
	s_mov_b32 s21, s17
	s_add_i32 s9, s13, s8
	v_lshl_add_u64 v[84:85], v[182:183], 0, s[20:21]
	v_lshlrev_b32_e32 v187, 3, v44
	s_mov_b32 s14, s20
	v_and_b32_e32 v176, 24, v187
	v_writelane_b32 v254, s14, 52
	v_lshlrev_b32_e32 v2, 1, v176
	v_lshl_add_u64 v[4:5], v[4:5], 0, v[2:3]
	v_writelane_b32 v254, s15, 53
	v_and_b32_e32 v185, 31, v44
	v_readlane_b32 s26, v254, 54
	v_lshl_add_u64 v[180:181], v[4:5], 0, s[24:25]
	v_readlane_b32 s27, v254, 55
	v_bfe_u32 v186, v44, 5, 1
	s_add_i32 s8, s9, 0x6000
	v_lshl_add_u64 v[4:5], v[180:181], 0, s[20:21]
	s_mov_b32 s14, m0
	s_mov_b32 m0, s8
	s_nop 0
	global_load_lds_dwordx4 v[4:5], off
	s_mov_b32 m0, s14
	s_mov_b32 s27, s17
	v_lshlrev_b32_e32 v2, 11, v185
	v_lshl_add_u64 v[4:5], v[182:183], 0, s[26:27]
	s_add_i32 s14, s9, 0x2000
	v_lshl_or_b32 v2, v186, 4, v2
	v_lshlrev_b32_e32 v188, 10, v186
	v_lshlrev_b32_e32 v4, 4, v185
	v_add3_u32 v189, 0, v188, v4
	v_mov_b32_e32 v4, v3
	v_mov_b32_e32 v5, v3
	v_mov_b32_e32 v6, v3
	v_mov_b32_e32 v7, v3
	v_mov_b32_e32 v8, v3
	v_mov_b32_e32 v9, v3
	v_mov_b32_e32 v10, v3
	v_mov_b32_e32 v11, v3
	v_mov_b32_e32 v12, v3
	v_mov_b32_e32 v13, v3
	v_mov_b32_e32 v14, v3
	v_mov_b32_e32 v15, v3
	v_mov_b32_e32 v16, v3
	v_mov_b32_e32 v17, v3
	v_mov_b32_e32 v2, v3
	v_mov_b64_e32 v[18:19], v[16:17]
	v_mov_b64_e32 v[16:17], v[14:15]
	v_mov_b64_e32 v[14:15], v[12:13]
	v_mov_b64_e32 v[12:13], v[10:11]
	v_mov_b64_e32 v[10:11], v[8:9]
	v_mov_b64_e32 v[8:9], v[6:7]
	v_mov_b64_e32 v[6:7], v[4:5]
	v_mov_b64_e32 v[4:5], v[2:3]
	s_mov_b64 s[14:15], 0x10000
	v_lshl_add_u64 v[20:21], v[84:85], 0, s[14:15]
	s_add_i32 s14, s9, 0x4000
	s_waitcnt vmcnt(0) lgkmcnt(0)
	s_barrier
; #define WAIT_BAR(N) asm volatile("s_waitcnt vmcnt(" #N ") lgkmcnt(0)\n\ts_barrier":::"memory")
;   #define DMA_K(t,slot) glds16(ksrc+(long)(((t)+t0)&(NT-1))*KVBLK*KVP,(unsigned)__builtin_amdgcn_readfirstlane(kdst+(slot)))
;   #define DMA_V(t,slot) glds16(vsrc+(long)(((t)+t0)&(NT-1))*KVBLK*KVP,(unsigned)__builtin_amdgcn_readfirstlane(vdst+(slot)))
;   #define CMASK(P0,P1,t) do{}while(0)
;   #define START(P0,P1) do{ const float rm=rowmax(P0,P1); resc=false; \
;     { const float dl=rm; mhat=fadd_s(mhat,dl); \
;       _Pragma("unroll") for(int r=0;r<16;++r){P0[r]=fsub_s(P0[r],dl);P1[r]=fsub_s(P1[r],dl);} \
;       _Pragma("unroll") for(int r=0;r<16;++r)negm[r]=-mhat; asm volatile("":"+v"(negm)); } \
;     _Pragma("unroll") for(int r=0;r<16;++r)P0[r]=__builtin_amdgcn_exp2f(P0[r]); }while(0)
;   #define ROT() do{sl_prev=sl_cur;sl_cur=sl_next;sl_next=(sl_next==(NSLOT-1)*SLOTB)?0:sl_next+SLOTB;}while(0)
;   #define CMASK(P0,P1,t) do{}while(0)
;   #define CMASK(P0,P1,t) do{}while(0)
; template<int THRL,bool NOMAX> __device__ __forceinline__ void attn_unit(int b,int h,int qb,int t0,const bf16*Q,const bf16*__restrict__ KV,const bf16*__restrict__ GA,bf16*O,char*shm){
;     ...
;   WAIT_BAR(3);
;   qkt(pA0,pA1,Kbase,qr,negm,r32,hi);asm volatile("s_nop 15\n\ts_nop 7":"+v"(pA0),"+v"(pA1));CMASK(pA0,pA1,0);
;   START(pA0,pA1);
;   _Pragma("unroll") for(int r=0;r<16;++r)pA1[r]=__builtin_amdgcn_exp2f(pA1[r]);
;   WAIT_BAR(0);
;   DMA_K(3,0);DMA_V(1,SLOTB);
;   ROT();
;   kload8(kf,kp0+sl_cur);
;   WAIT_BAR(2);
;   s16x4 vlo[8],vhi[8]; u32x4 pw0,pw1,pw2,pw3;
	ds_read_b128 v[36:39], v189
	ds_read_b128 v[40:43], v189 offset:512
	s_waitcnt vmcnt(3) lgkmcnt(1)
	v_mfma_f32_32x32x16_bf16 v[20:35], v[36:39], v[152:155], v[4:19]
	v_lshlrev_b32_e32 v2, 1, v44
	v_and_b32_e32 v177, 32, v2
	s_mov_b64 s[20:21], 0x18000
	v_mov_b32_e32 v191, 0
	s_mov_b32 s14, -1
	s_mov_b32 s16, 0
	s_movk_i32 s22, 0x2000
	s_waitcnt lgkmcnt(0)
	v_mfma_f32_32x32x16_bf16 v[4:19], v[40:43], v[152:155], v[4:19]
	ds_read_b128 v[36:39], v189 offset:2048
	ds_read_b128 v[40:43], v189 offset:2560
	s_movk_i32 s15, 0x4000
	s_waitcnt vmcnt(2) lgkmcnt(1)
	v_mfma_f32_32x32x16_bf16 v[20:35], v[36:39], v[144:147], v[20:35]
	s_waitcnt lgkmcnt(0)
	v_mfma_f32_32x32x16_bf16 v[4:19], v[40:43], v[144:147], v[4:19]
	ds_read_b128 v[36:39], v189 offset:4096
	ds_read_b128 v[40:43], v189 offset:4608
	s_waitcnt vmcnt(1) lgkmcnt(1)
	v_mfma_f32_32x32x16_bf16 v[20:35], v[36:39], v[136:139], v[20:35]
	ds_read_b128 v[36:39], v189 offset:6144
	s_waitcnt lgkmcnt(1)
	v_mfma_f32_32x32x16_bf16 v[4:19], v[40:43], v[136:139], v[4:19]
	ds_read_b128 v[40:43], v189 offset:6656
	s_waitcnt vmcnt(0) lgkmcnt(1)
	v_mfma_f32_32x32x16_bf16 v[20:35], v[36:39], v[132:135], v[20:35]
	v_lshlrev_b32_e32 v36, 4, v44
	v_and_b32_e32 v2, 0xc0, v36
	v_lshl_or_b32 v178, v186, 8, v2
	v_add_u32_e32 v2, 0, v177
	v_add3_u32 v2, v2, v176, v178
	s_waitcnt lgkmcnt(0)
	v_mfma_f32_32x32x16_bf16 v[4:19], v[40:43], v[132:135], v[4:19]
	s_nop 15
	s_nop 7
	s_nop 0
	v_max3_f32 v36, v20, v21, v4
	v_max3_f32 v37, v22, v23, v5
	s_nop 0
	v_max3_f32 v36, v36, v6, v7
	v_max3_f32 v37, v37, v26, v27
	s_nop 0
	v_max3_f32 v36, v36, v24, v25
	v_max3_f32 v37, v37, v10, v11
	s_nop 0
	v_max3_f32 v36, v36, v8, v9
	v_max3_f32 v37, v37, v30, v31
	s_nop 0
	v_max3_f32 v36, v36, v28, v29
	v_max3_f32 v37, v37, v14, v15
	s_nop 0
	v_max3_f32 v36, v36, v12, v13
	v_max3_f32 v37, v37, v34, v35
	s_nop 0
	v_max3_f32 v36, v36, v32, v33
	v_max3_f32 v37, v37, v18, v19
	s_nop 0
	v_max3_f32 v36, v36, v16, v17
	s_nop 0
	v_max_f32_e32 v36, v36, v37
	s_nop 0
	v_mov_b32_e32 v37, v36
	s_nop 1
	v_permlane32_swap_b32_e32 v36, v37
	v_max_f32_e32 v36, v36, v37
	s_nop 0
	v_add_f32_e32 v37, v3, v36
	v_sub_f32_e32 v20, v20, v36
	v_sub_f32_e32 v4, v4, v36
	v_sub_f32_e32 v21, v21, v36
	v_sub_f32_e32 v5, v5, v36
	v_sub_f32_e32 v22, v22, v36
	v_sub_f32_e32 v6, v6, v36
	v_sub_f32_e32 v23, v23, v36
	v_sub_f32_e32 v7, v7, v36
	v_sub_f32_e32 v24, v24, v36
	v_sub_f32_e32 v8, v8, v36
	v_sub_f32_e32 v25, v25, v36
	v_sub_f32_e32 v9, v9, v36
	v_sub_f32_e32 v26, v26, v36
	v_sub_f32_e32 v10, v10, v36
	v_sub_f32_e32 v27, v27, v36
	v_sub_f32_e32 v11, v11, v36
	v_sub_f32_e32 v28, v28, v36
	v_sub_f32_e32 v12, v12, v36
	v_sub_f32_e32 v29, v29, v36
	v_sub_f32_e32 v13, v13, v36
	v_sub_f32_e32 v30, v30, v36
	v_sub_f32_e32 v14, v14, v36
	v_sub_f32_e32 v31, v31, v36
	v_sub_f32_e32 v15, v15, v36
	v_sub_f32_e32 v32, v32, v36
	v_sub_f32_e32 v16, v16, v36
	v_sub_f32_e32 v33, v33, v36
	v_sub_f32_e32 v17, v17, v36
	v_sub_f32_e32 v34, v34, v36
	v_sub_f32_e32 v18, v18, v36
	v_sub_f32_e32 v35, v35, v36
	v_sub_f32_e32 v19, v19, v36
	s_nop 0
	v_xor_b32_e32 v36, 0x80000000, v37
	v_mov_b32_e32 v37, v36
	v_mov_b32_e32 v38, v36
	v_mov_b32_e32 v39, v36
	v_mov_b32_e32 v40, v36
	v_mov_b32_e32 v41, v36
	v_mov_b32_e32 v42, v36
	v_mov_b32_e32 v43, v36
	v_mov_b32_e32 v44, v36
	v_mov_b32_e32 v45, v36
	v_mov_b32_e32 v46, v36
	v_mov_b32_e32 v47, v36
	v_mov_b32_e32 v48, v36
	v_mov_b32_e32 v49, v36
	v_mov_b32_e32 v50, v36
	v_mov_b32_e32 v51, v36
	s_waitcnt vmcnt(0) lgkmcnt(0)
	s_barrier
	v_exp_f32_e32 v52, v4
	v_exp_f32_e32 v53, v5
	v_lshl_add_u64 v[4:5], v[84:85], 0, s[20:21]
	s_mov_b32 s20, m0
	s_mov_b32 m0, s9
	s_nop 0
	global_load_lds_dwordx4 v[4:5], off
	s_mov_b32 m0, s20
	s_mov_b32 s20, s26
	v_writelane_b32 v254, s20, 54
	v_lshl_add_u64 v[4:5], v[180:181], 0, s[26:27]
	v_exp_f32_e32 v68, v20
	v_writelane_b32 v254, s21, 55
	s_add_i32 s20, s9, 0x8000
	s_mov_b32 s21, m0
	s_mov_b32 m0, s20
	s_nop 0
	global_load_lds_dwordx4 v[4:5], off
	s_mov_b32 m0, s21
	ds_read_b128 v[84:87], v189 offset:8192
	ds_read_b128 v[168:171], v189 offset:8704
	ds_read_b128 v[172:175], v189 offset:10240
	ds_read_b128 v[164:167], v189 offset:10752
	ds_read_b128 v[128:131], v189 offset:12288
	ds_read_b128 v[124:127], v189 offset:12800
	ds_read_b128 v[120:123], v189 offset:14336
	ds_read_b128 v[116:119], v189 offset:14848
	v_exp_f32_e32 v69, v21
	v_exp_f32_e32 v70, v22
	v_exp_f32_e32 v71, v23
	v_exp_f32_e32 v72, v24
	v_exp_f32_e32 v73, v25
	v_exp_f32_e32 v74, v26
	v_exp_f32_e32 v75, v27
	v_exp_f32_e32 v76, v28
	v_exp_f32_e32 v77, v29
	v_exp_f32_e32 v78, v30
	v_exp_f32_e32 v79, v31
	v_exp_f32_e32 v80, v32
	v_exp_f32_e32 v81, v33
	v_exp_f32_e32 v82, v34
	v_exp_f32_e32 v83, v35
	v_exp_f32_e32 v54, v6
	v_exp_f32_e32 v55, v7
	v_exp_f32_e32 v56, v8
	v_exp_f32_e32 v57, v9
	v_exp_f32_e32 v58, v10
	v_exp_f32_e32 v59, v11
	v_exp_f32_e32 v60, v12
	v_exp_f32_e32 v61, v13
	v_exp_f32_e32 v62, v14
	v_exp_f32_e32 v63, v15
	v_exp_f32_e32 v64, v16
	v_exp_f32_e32 v65, v17
	v_exp_f32_e32 v66, v18
	v_exp_f32_e32 v67, v19
	s_waitcnt vmcnt(2) lgkmcnt(0)
	s_barrier
	v_readlane_b32 s20, v254, 35
	v_readlane_b32 s21, v254, 33
	v_mov_b32_e32 v4, 0
	v_mov_b32_e32 v5, v191
	v_mov_b32_e32 v6, v191
	v_mov_b32_e32 v7, v191
	v_mov_b32_e32 v8, v191
	v_mov_b32_e32 v9, v191
	v_mov_b32_e32 v10, v191
	v_mov_b32_e32 v11, v191
	v_mov_b32_e32 v12, v191
	v_mov_b32_e32 v13, v191
	v_mov_b32_e32 v14, v191
	v_mov_b32_e32 v15, v191
	v_mov_b32_e32 v16, v191
	v_mov_b32_e32 v17, v191
	v_mov_b32_e32 v18, v191
	v_mov_b32_e32 v19, v191
	v_mov_b32_e32 v20, 0
	v_mov_b32_e32 v21, v191
	v_mov_b32_e32 v22, v191
	v_mov_b32_e32 v23, v191
	v_mov_b32_e32 v24, v191
	v_mov_b32_e32 v25, v191
	v_mov_b32_e32 v26, v191
	v_mov_b32_e32 v27, v191
	v_mov_b32_e32 v28, v191
	v_mov_b32_e32 v29, v191
	v_mov_b32_e32 v30, v191
	v_mov_b32_e32 v31, v191
	v_mov_b32_e32 v32, v191
	v_mov_b32_e32 v33, v191
	v_mov_b32_e32 v34, v191
	v_mov_b32_e32 v35, v191
